# attention tile loop: second QK chain scores consumed in place from v[216:231], eight v_mov_b64 copies per iteration removed
# speedup vs baseline: 1.0102x; 1.0026x over previous
.LBB0_421:
	s_lshl_b64 s[4:5], s[4:5], 1
	v_lshl_add_u64 v[0:1], v[186:187], 0, s[4:5]
	global_load_dwordx4 v[160:163], v[0:1], off
	global_load_dwordx4 v[164:167], v[0:1], off offset:32
	global_load_dwordx4 v[168:171], v[0:1], off offset:64
	global_load_dwordx4 v[172:175], v[0:1], off offset:96
	s_xor_b64 s[30:31], s[6:7], -1
	s_add_u32 s36, s73, s4
	s_addc_u32 s37, s74, s5
	v_lshl_add_u64 v[0:1], v[180:181], 1, s[36:37]
	s_mov_b32 s4, m0
	s_mov_b32 m0, s43
	s_nop 0
	global_load_lds_dwordx4 v[0:1], off
	s_mov_b32 m0, s4
	v_lshl_add_u64 v[0:1], v[0:1], 0, s[22:23]
	s_mov_b32 s4, m0
	s_mov_b32 m0, s64
	s_nop 0
	global_load_lds_dwordx4 v[0:1], off
	s_mov_b32 m0, s4
	v_add_u32_e32 v4, 0, v206
	s_mov_b32 s4, m0
	s_mov_b32 m0, s65
	s_nop 0
	global_load_lds_dwordx4 v[190:191], off
	s_mov_b32 m0, s4
	v_add_u32_e32 v8, 0, v207
	s_mov_b32 s4, m0
	s_mov_b32 m0, s66
	s_nop 0
	global_load_lds_dwordx4 v[192:193], off
	s_mov_b32 m0, s4
	s_waitcnt vmcnt(0)
	s_barrier
	v_add_u32_e32 v9, 0, v209
	s_mov_b32 s4, 0
	s_mov_b32 s5, s4
	s_mov_b32 s6, s4
	s_mov_b32 s7, s4
	s_mov_b32 s8, s4
	s_mov_b32 s9, s4
	s_mov_b32 s10, s4
	s_mov_b32 s11, s4
	s_mov_b32 s12, s4
	s_mov_b32 s13, s4
	s_mov_b32 s14, s4
	s_mov_b32 s15, s4
	s_mov_b32 s16, s4
	s_mov_b32 s17, s4
	s_mov_b32 s18, s4
	s_mov_b32 s19, s4
	v_mov_b32_e32 v196, 0
	s_movk_i32 s77, 0x4000
	s_movk_i32 s76, 0x2000
	s_mov_b32 s75, 0x20000
	s_mov_b64 s[38:39], s[28:29]
	s_waitcnt vmcnt(0)
	ds_read_b128 v[0:3], v4
	ds_read_b128 v[4:7], v4 offset:4096
	s_waitcnt lgkmcnt(1)
	v_mfma_f32_32x32x16_bf16 v[64:79], v[0:3], v[160:163], 0
	s_waitcnt lgkmcnt(0)
	v_mfma_f32_32x32x16_bf16 v[80:95], v[4:7], v[160:163], 0
	ds_read_b128 v[0:3], v8
	ds_read_b128 v[4:7], v8 offset:4096
	v_add_u32_e32 v8, 0, v208
	s_waitcnt lgkmcnt(1)
	v_mfma_f32_32x32x16_bf16 v[64:79], v[0:3], v[164:167], v[64:79]
	ds_read_b128 v[0:3], v8
	s_waitcnt lgkmcnt(1)
	v_mfma_f32_32x32x16_bf16 v[80:95], v[4:7], v[164:167], v[80:95]
	ds_read_b128 v[4:7], v8 offset:4096
	s_waitcnt lgkmcnt(1)
	v_mfma_f32_32x32x16_bf16 v[64:79], v[0:3], v[168:171], v[64:79]
	ds_read_b128 v[0:3], v9
	s_waitcnt lgkmcnt(1)
	v_mfma_f32_32x32x16_bf16 v[80:95], v[4:7], v[168:171], v[80:95]
	ds_read_b128 v[4:7], v9 offset:4096
	s_waitcnt lgkmcnt(1)
	v_mfma_f32_32x32x16_bf16 v[64:79], v[0:3], v[172:175], v[64:79]
	s_waitcnt lgkmcnt(0)
	v_mfma_f32_32x32x16_bf16 v[80:95], v[4:7], v[172:175], v[80:95]
	s_nop 9
	v_max_f32_e32 v0, v65, v65
	v_max_f32_e32 v1, v64, v64
	v_max_f32_e32 v0, v1, v0
	v_max3_f32 v0, v0, v66, v67
	v_max3_f32 v0, v0, v68, v69
	v_max3_f32 v0, v0, v70, v71
	v_max3_f32 v0, v0, v72, v73
	v_max3_f32 v0, v0, v74, v75
	v_max3_f32 v0, v0, v76, v77
	v_max3_f32 v0, v0, v78, v79
	v_max3_f32 v0, v0, v80, v81
	v_max3_f32 v0, v0, v82, v83
	v_max3_f32 v0, v0, v84, v85
	v_max3_f32 v0, v0, v86, v87
	v_max3_f32 v0, v0, v88, v89
	v_max3_f32 v0, v0, v90, v91
	v_max3_f32 v0, v0, v92, v93
	v_max3_f32 v197, v0, v94, v95
	ds_bpermute_b32 v96, v204, v197
	v_mov_b64_e32 v[0:1], s[4:5]
	v_mov_b64_e32 v[14:15], s[18:19]
	v_mov_b64_e32 v[2:3], s[6:7]
	v_mov_b64_e32 v[4:5], s[8:9]
	s_waitcnt lgkmcnt(0)
	v_max_f32_e32 v96, v96, v96
	v_max_f32_e32 v195, v197, v96
	v_mov_b64_e32 v[6:7], s[10:11]
	v_mov_b64_e32 v[8:9], s[12:13]
	v_mov_b64_e32 v[10:11], s[14:15]
	v_mov_b64_e32 v[12:13], s[16:17]
	v_mov_b64_e32 v[30:31], v[14:15]
	v_mov_b64_e32 v[46:47], v[14:15]
	v_mov_b64_e32 v[62:63], v[14:15]
	v_sub_f32_e32 v112, v64, v195
	v_xor_b32_e32 v64, 0x80000000, v195
	v_mov_b64_e32 v[28:29], v[12:13]
	v_mov_b64_e32 v[26:27], v[10:11]
	v_mov_b64_e32 v[24:25], v[8:9]
	v_mov_b64_e32 v[22:23], v[6:7]
	v_mov_b64_e32 v[20:21], v[4:5]
	v_mov_b64_e32 v[18:19], v[2:3]
	v_mov_b64_e32 v[16:17], v[0:1]
	v_mov_b64_e32 v[44:45], v[12:13]
	v_mov_b64_e32 v[42:43], v[10:11]
	v_mov_b64_e32 v[40:41], v[8:9]
	v_mov_b64_e32 v[38:39], v[6:7]
	v_mov_b64_e32 v[36:37], v[4:5]
	v_mov_b64_e32 v[34:35], v[2:3]
	v_mov_b64_e32 v[32:33], v[0:1]
	v_mov_b64_e32 v[60:61], v[12:13]
	v_mov_b64_e32 v[58:59], v[10:11]
	v_mov_b64_e32 v[56:57], v[8:9]
	v_mov_b64_e32 v[54:55], v[6:7]
	v_mov_b64_e32 v[52:53], v[4:5]
	v_mov_b64_e32 v[50:51], v[2:3]
	v_mov_b64_e32 v[48:49], v[0:1]
	v_sub_f32_e32 v127, v79, v195
	v_sub_f32_e32 v126, v78, v195
	v_sub_f32_e32 v125, v77, v195
	v_sub_f32_e32 v124, v76, v195
	v_sub_f32_e32 v123, v75, v195
	v_sub_f32_e32 v122, v74, v195
	v_sub_f32_e32 v121, v73, v195
	v_sub_f32_e32 v120, v72, v195
	v_sub_f32_e32 v119, v71, v195
	v_sub_f32_e32 v118, v70, v195
	v_sub_f32_e32 v117, v69, v195
	v_sub_f32_e32 v116, v68, v195
	v_sub_f32_e32 v115, v67, v195
	v_sub_f32_e32 v114, v66, v195
	v_sub_f32_e32 v113, v65, v195
	v_sub_f32_e32 v231, v95, v195
	v_sub_f32_e32 v230, v94, v195
	v_sub_f32_e32 v229, v93, v195
	v_sub_f32_e32 v228, v92, v195
	v_sub_f32_e32 v227, v91, v195
	v_sub_f32_e32 v226, v90, v195
	v_sub_f32_e32 v225, v89, v195
	v_sub_f32_e32 v224, v88, v195
	v_sub_f32_e32 v223, v87, v195
	v_sub_f32_e32 v222, v86, v195
	v_sub_f32_e32 v221, v85, v195
	v_sub_f32_e32 v220, v84, v195
	v_sub_f32_e32 v219, v83, v195
	v_sub_f32_e32 v218, v82, v195
	v_sub_f32_e32 v217, v81, v195
	v_sub_f32_e32 v216, v80, v195
	v_mov_b32_e32 v65, v64
	v_mov_b32_e32 v66, v64
	v_mov_b32_e32 v67, v64
	v_mov_b32_e32 v68, v64
	v_mov_b32_e32 v69, v64
	v_mov_b32_e32 v70, v64
	v_mov_b32_e32 v71, v64
	v_mov_b32_e32 v72, v64
	v_mov_b32_e32 v73, v64
	v_mov_b32_e32 v74, v64
	v_mov_b32_e32 v75, v64
	v_mov_b32_e32 v76, v64
	v_mov_b32_e32 v77, v64
	v_mov_b32_e32 v78, v64
	v_mov_b32_e32 v79, v64
	s_cmp_gt_u32 s4, 33
	s_cselect_b64 s[6:7], -1, 0
	s_cmp_lt_u32 s4, 34
	s_cselect_b32 s20, s75, 0x230000
	s_lshl_b64 s[8:9], s[20:21], 1
	s_add_u32 s8, s36, s8
	s_addc_u32 s9, s37, s9
	s_add_i32 s5, s77, 0
	s_branch .LBB0_424

.LBB0_423:
	v_add_u32_e32 v81, s5, v206
	ds_read_b128 v[82:85], v81
	ds_read_b128 v[86:89], v81 offset:4096
	v_add_u32_e32 v90, s5, v207
	v_add_u32_e32 v94, s5, v208
	v_exp_f32_e32 v128, v128
	v_exp_f32_e32 v129, v129
	v_exp_f32_e32 v152, v96
	v_exp_f32_e32 v153, v97
	v_exp_f32_e32 v108, v108
	v_exp_f32_e32 v109, v109
	v_exp_f32_e32 v110, v110
	v_exp_f32_e32 v111, v111
	v_add_f32_e32 v154, v153, v152
	v_add_u32_e32 v81, s5, v209
	s_waitcnt lgkmcnt(1)
	v_mfma_f32_32x32x16_bf16 v[112:127], v[82:85], v[160:163], v[64:79]
	ds_read_b128 v[82:85], v90
	ds_read_b128 v[90:93], v90 offset:4096
	ds_read_b128 v[144:147], v94
	ds_read_b128 v[148:151], v94 offset:4096
	s_add_i32 s4, s4, 2
	s_waitcnt lgkmcnt(4)
	v_mfma_f32_32x32x16_bf16 v[216:231], v[86:89], v[160:163], v[64:79]
	ds_read_b128 v[86:89], v81
	ds_read_b128 v[94:97], v81 offset:4096
	v_add_f32_e32 v81, v129, v128
	v_add_f32_e32 v81, v154, v81
	v_cvt_pk_bf16_f32 v128, v128, v129
	s_add_i32 s5, s76, s77
	s_cmpk_eq_i32 s5, 0x2000
	s_waitcnt lgkmcnt(5)
	v_mfma_f32_32x32x16_bf16 v[112:127], v[82:85], v[164:167], v[112:127]
	v_exp_f32_e32 v83, v130
	v_exp_f32_e32 v84, v131
	v_exp_f32_e32 v85, v98
	v_exp_f32_e32 v98, v99
	v_exp_f32_e32 v99, v103
	v_cvt_pk_bf16_f32 v129, v83, v84
	v_exp_f32_e32 v103, v137
	s_waitcnt lgkmcnt(4)
	v_mfma_f32_32x32x16_bf16 v[216:231], v[90:93], v[164:167], v[216:231]
	v_add_f32_e32 v90, v84, v83
	v_add_f32_e32 v91, v98, v85
	v_add_f32_e32 v90, v91, v90
	v_add_f32_e32 v81, v90, v81
	v_exp_f32_e32 v90, v132
	v_exp_f32_e32 v91, v133
	v_exp_f32_e32 v92, v100
	v_exp_f32_e32 v93, v101
	s_waitcnt lgkmcnt(3)
	v_mfma_f32_32x32x16_bf16 v[112:127], v[144:147], v[168:171], v[112:127]
	v_cvt_pk_bf16_f32 v83, v85, v98
	v_add_f32_e32 v84, v91, v90
	v_add_f32_e32 v85, v93, v92
	v_add_f32_e32 v84, v85, v84
	v_cvt_pk_bf16_f32 v130, v90, v91
	v_exp_f32_e32 v85, v134
	v_exp_f32_e32 v90, v135
	s_waitcnt lgkmcnt(2)
	v_mfma_f32_32x32x16_bf16 v[216:231], v[148:151], v[168:171], v[216:231]
	v_exp_f32_e32 v98, v102
	v_add_f32_e32 v81, v84, v81
	v_add_f32_e32 v91, v90, v85
	v_exp_f32_e32 v102, v136
	v_exp_f32_e32 v136, v104
	v_exp_f32_e32 v137, v105
	v_cvt_pk_bf16_f32 v84, v92, v93
	s_waitcnt lgkmcnt(1)
	v_mfma_f32_32x32x16_bf16 v[112:127], v[86:89], v[172:175], v[112:127]
	v_add_f32_e32 v86, v99, v98
	v_add_f32_e32 v86, v86, v91
	v_add_f32_e32 v81, v86, v81
	ds_read_b64_tr_b16 v[86:87], v213 offset:40960
	ds_read_b64_tr_b16 v[88:89], v213 offset:43008
	v_cvt_pk_bf16_f32 v131, v85, v90
	v_add_f32_e32 v104, v103, v102
	v_add_f32_e32 v105, v137, v136
	s_waitcnt lgkmcnt(2)
	v_mfma_f32_32x32x16_bf16 v[216:231], v[94:97], v[172:175], v[216:231]
	ds_read_b64_tr_b16 v[90:91], v214 offset:40960
	ds_read_b64_tr_b16 v[92:93], v214 offset:43008
	ds_read_b64_tr_b16 v[94:95], v213 offset:45056
	ds_read_b64_tr_b16 v[96:97], v213 offset:47104
	v_cvt_pk_bf16_f32 v85, v98, v99
	v_cvt_pk_bf16_f32 v82, v152, v153
	s_cselect_b32 s8, s71, 0x2000
	s_cmpk_lg_i32 s5, 0x6000
	s_cselect_b32 s77, s8, 0
	s_add_u32 s38, s38, 0x40000
	s_waitcnt lgkmcnt(2)
	v_mfma_f32_32x32x16_bf16 v[32:47], v[90:93], v[128:131], v[32:47]
	v_add_f32_e32 v90, v105, v104
	v_add_f32_e32 v81, v90, v81
	v_cvt_pk_bf16_f32 v90, v102, v103
	v_exp_f32_e32 v91, v138
	v_exp_f32_e32 v92, v139
	v_exp_f32_e32 v138, v106
	v_exp_f32_e32 v106, v140
	v_mfma_f32_32x32x16_bf16 v[48:63], v[86:89], v[128:131], v[48:63]
	ds_read_b64_tr_b16 v[86:87], v215 offset:40960
	ds_read_b64_tr_b16 v[88:89], v215 offset:43008
	ds_read_b64_tr_b16 v[98:99], v214 offset:45056
	ds_read_b64_tr_b16 v[100:101], v214 offset:47104
	ds_read_b64_tr_b16 v[102:103], v248 offset:40960
	ds_read_b64_tr_b16 v[104:105], v248 offset:43008
	ds_read_b64_tr_b16 v[132:133], v215 offset:45056
	ds_read_b64_tr_b16 v[134:135], v215 offset:47104
	v_exp_f32_e32 v139, v107
	s_addc_u32 s39, s39, 0
	s_add_i32 s75, s75, 0x20000
	s_and_b64 vcc, exec, s[6:7]
	s_waitcnt lgkmcnt(2)
	v_mfma_f32_32x32x16_bf16 v[0:15], v[102:105], v[128:131], v[0:15]
	v_exp_f32_e32 v102, v141
	v_exp_f32_e32 v103, v142
	v_exp_f32_e32 v104, v143
	v_add_f32_e32 v105, v92, v91
	v_cvt_pk_bf16_f32 v91, v91, v92
	v_cvt_pk_bf16_f32 v92, v106, v102
	v_cvt_pk_bf16_f32 v93, v103, v104
	v_mfma_f32_32x32x16_bf16 v[16:31], v[86:89], v[128:131], v[16:31]
	ds_read_b64_tr_b16 v[86:87], v248 offset:45056
	ds_read_b64_tr_b16 v[88:89], v248 offset:47104
	v_mfma_f32_32x32x16_bf16 v[48:63], v[94:97], v[90:93], v[48:63]
	v_add_f32_e32 v94, v139, v138
	v_add_f32_e32 v94, v94, v105
	v_add_f32_e32 v81, v94, v81
	v_add_f32_e32 v94, v102, v106
	v_add_f32_e32 v95, v109, v108
	v_add_f32_e32 v94, v95, v94
	v_add_f32_e32 v81, v94, v81
	v_mfma_f32_32x32x16_bf16 v[32:47], v[98:101], v[90:93], v[32:47]
	v_add_f32_e32 v94, v104, v103
	v_add_f32_e32 v95, v111, v110
	v_add_f32_e32 v94, v95, v94
	v_add_f32_e32 v106, v94, v81
	v_max_f32_e32 v81, v113, v113
	v_max_f32_e32 v94, v112, v112
	v_max_f32_e32 v81, v94, v81
	s_waitcnt lgkmcnt(2)
	v_mfma_f32_32x32x16_bf16 v[16:31], v[132:135], v[90:93], v[16:31]
	ds_read_b64_tr_b16 v[94:95], v213 offset:49152
	ds_read_b64_tr_b16 v[96:97], v213 offset:51200
	v_max3_f32 v81, v81, v114, v115
	v_max3_f32 v81, v81, v116, v117
	v_max3_f32 v81, v81, v118, v119
	v_max3_f32 v81, v81, v120, v121
	v_max3_f32 v81, v81, v122, v123
	v_max3_f32 v81, v81, v124, v125
	s_waitcnt lgkmcnt(2)
	v_mfma_f32_32x32x16_bf16 v[0:15], v[86:89], v[90:93], v[0:15]
	ds_read_b64_tr_b16 v[86:87], v214 offset:49152
	ds_read_b64_tr_b16 v[88:89], v214 offset:51200
	ds_read_b64_tr_b16 v[90:91], v213 offset:53248
	ds_read_b64_tr_b16 v[92:93], v213 offset:55296
	v_max3_f32 v81, v81, v126, v127
	v_max3_f32 v81, v81, v216, v217
	v_max3_f32 v81, v81, v218, v219
	v_max3_f32 v81, v81, v220, v221
	v_max3_f32 v81, v81, v222, v223
	v_max3_f32 v81, v81, v224, v225
	s_waitcnt lgkmcnt(4)
	v_mfma_f32_32x32x16_bf16 v[48:63], v[94:97], v[82:85], v[48:63]
	ds_read_b64_tr_b16 v[94:95], v215 offset:49152
	ds_read_b64_tr_b16 v[96:97], v215 offset:51200
	ds_read_b64_tr_b16 v[98:99], v214 offset:53248
	ds_read_b64_tr_b16 v[100:101], v214 offset:55296
	v_max3_f32 v81, v81, v226, v227
	v_max3_f32 v81, v81, v228, v229
	v_max3_f32 v107, v81, v230, v231
	v_add_f32_e32 v196, v194, v106
	v_add_f32_e32 v197, v195, v107
	s_waitcnt lgkmcnt(6)
	v_mfma_f32_32x32x16_bf16 v[32:47], v[86:89], v[82:85], v[32:47]
	ds_read_b64_tr_b16 v[86:87], v248 offset:49152
	ds_read_b64_tr_b16 v[88:89], v248 offset:51200
	ds_read_b64_tr_b16 v[102:103], v215 offset:53248
	ds_read_b64_tr_b16 v[104:105], v215 offset:55296
	s_waitcnt lgkmcnt(6)
	v_mfma_f32_32x32x16_bf16 v[16:31], v[94:97], v[82:85], v[16:31]
	ds_read_b64_tr_b16 v[94:95], v248 offset:53248
	ds_read_b64_tr_b16 v[96:97], v248 offset:55296
	s_waitcnt vmcnt(0)
	s_waitcnt lgkmcnt(4)
	v_mfma_f32_32x32x16_bf16 v[0:15], v[86:89], v[82:85], v[0:15]
	v_cvt_pk_bf16_f32 v85, v110, v111
	v_cvt_pk_bf16_f32 v84, v108, v109
	v_cvt_pk_bf16_f32 v83, v138, v139
	v_cvt_pk_bf16_f32 v82, v136, v137
	s_nop 1
	v_mfma_f32_32x32x16_bf16 v[48:63], v[90:93], v[82:85], v[48:63]
	s_waitcnt lgkmcnt(0)
	s_barrier
	v_mfma_f32_32x32x16_bf16 v[32:47], v[98:101], v[82:85], v[32:47]
	s_cmp_gt_u32 s4, 33
	s_cselect_b64 s[6:7], -1, 0
	s_cmp_lt_u32 s4, 34
	s_cselect_b32 s20, s75, 0x230000
	v_mfma_f32_32x32x16_bf16 v[16:31], v[102:105], v[82:85], v[16:31]
	s_lshl_b64 s[8:9], s[20:21], 1
	s_add_u32 s8, s36, s8
	s_addc_u32 s9, s37, s9
	s_add_i32 s5, s77, 0
	v_mfma_f32_32x32x16_bf16 v[0:15], v[94:97], v[82:85], v[0:15]
	s_cbranch_vccnz .LBB0_432
.LBB0_424:
	v_add_u32_e32 v86, s76, v206
	ds_read_b128 v[82:85], v86
	ds_read_b128 v[86:89], v86 offset:4096
	v_lshl_add_u64 v[80:81], v[180:181], 1, s[8:9]
	s_add_i32 s8, s5, s42
	s_mov_b32 m0, s8
	s_nop 0
	global_load_lds_dwordx4 v[80:81], off
	v_lshl_add_u64 v[80:81], v[176:177], 1, s[38:39]
	s_mov_b32 m0, s67
	s_nop 0
	global_load_lds_dwordx4 v[80:81], off
	v_lshl_add_u64 v[80:81], v[178:179], 1, s[38:39]
	s_mov_b32 m0, s68
	s_nop 0
	global_load_lds_dwordx4 v[80:81], off
	v_add_f32_e32 v81, 0x41000000, v195
	v_cmp_gt_f32_e32 vcc, v197, v81
	s_cbranch_vccz .LBB0_428
	s_waitcnt lgkmcnt(0)
	ds_bpermute_b32 v80, v204, v197
	v_max_f32_e32 v82, v197, v197
	s_waitcnt lgkmcnt(0)
	v_max_f32_e32 v80, v80, v80
	v_max_f32_e32 v80, v82, v80
	v_mov_b64_e32 v[96:97], v[78:79]
	v_cmp_gt_f32_e32 vcc, v80, v81
	v_mov_b64_e32 v[94:95], v[76:77]
	v_mov_b64_e32 v[92:93], v[74:75]
	v_mov_b64_e32 v[90:91], v[72:73]
	v_mov_b64_e32 v[88:89], v[70:71]
	v_mov_b64_e32 v[86:87], v[68:69]
	v_mov_b64_e32 v[84:85], v[66:67]
	v_mov_b64_e32 v[82:83], v[64:65]
	s_and_saveexec_b64 s[8:9], vcc
	s_cbranch_execz .LBB0_427
	v_sub_f32_e32 v65, v80, v195
	v_exp_f32_e64 v64, -v65
	v_xor_b32_e32 v82, 0x80000000, v80
	v_sub_f32_e32 v127, v127, v65
	v_sub_f32_e32 v126, v126, v65
	v_mul_f32_e32 v196, v196, v64
	v_pk_mul_f32 v[62:63], v[62:63], v[64:65] op_sel_hi:[1,0]
	v_pk_mul_f32 v[60:61], v[60:61], v[64:65] op_sel_hi:[1,0]
	v_pk_mul_f32 v[58:59], v[58:59], v[64:65] op_sel_hi:[1,0]
	v_pk_mul_f32 v[56:57], v[56:57], v[64:65] op_sel_hi:[1,0]
	v_pk_mul_f32 v[54:55], v[54:55], v[64:65] op_sel_hi:[1,0]
	v_pk_mul_f32 v[52:53], v[52:53], v[64:65] op_sel_hi:[1,0]
	v_pk_mul_f32 v[50:51], v[50:51], v[64:65] op_sel_hi:[1,0]
	v_pk_mul_f32 v[48:49], v[48:49], v[64:65] op_sel_hi:[1,0]
	v_pk_mul_f32 v[46:47], v[46:47], v[64:65] op_sel_hi:[1,0]
	v_pk_mul_f32 v[44:45], v[44:45], v[64:65] op_sel_hi:[1,0]
	v_pk_mul_f32 v[42:43], v[42:43], v[64:65] op_sel_hi:[1,0]
	v_pk_mul_f32 v[40:41], v[40:41], v[64:65] op_sel_hi:[1,0]
	v_pk_mul_f32 v[38:39], v[38:39], v[64:65] op_sel_hi:[1,0]
	v_pk_mul_f32 v[36:37], v[36:37], v[64:65] op_sel_hi:[1,0]
	v_pk_mul_f32 v[34:35], v[34:35], v[64:65] op_sel_hi:[1,0]
	v_pk_mul_f32 v[32:33], v[32:33], v[64:65] op_sel_hi:[1,0]
	v_pk_mul_f32 v[30:31], v[30:31], v[64:65] op_sel_hi:[1,0]
	v_pk_mul_f32 v[28:29], v[28:29], v[64:65] op_sel_hi:[1,0]
	v_pk_mul_f32 v[26:27], v[26:27], v[64:65] op_sel_hi:[1,0]
	v_pk_mul_f32 v[24:25], v[24:25], v[64:65] op_sel_hi:[1,0]
	v_pk_mul_f32 v[22:23], v[22:23], v[64:65] op_sel_hi:[1,0]
	v_pk_mul_f32 v[20:21], v[20:21], v[64:65] op_sel_hi:[1,0]
	v_pk_mul_f32 v[18:19], v[18:19], v[64:65] op_sel_hi:[1,0]
	v_pk_mul_f32 v[16:17], v[16:17], v[64:65] op_sel_hi:[1,0]
	v_pk_mul_f32 v[14:15], v[14:15], v[64:65] op_sel_hi:[1,0]
	v_pk_mul_f32 v[12:13], v[12:13], v[64:65] op_sel_hi:[1,0]
	v_pk_mul_f32 v[10:11], v[10:11], v[64:65] op_sel_hi:[1,0]
	v_pk_mul_f32 v[8:9], v[8:9], v[64:65] op_sel_hi:[1,0]
	v_pk_mul_f32 v[6:7], v[6:7], v[64:65] op_sel_hi:[1,0]
	v_pk_mul_f32 v[4:5], v[4:5], v[64:65] op_sel_hi:[1,0]
	v_pk_mul_f32 v[2:3], v[2:3], v[64:65] op_sel_hi:[1,0]
	v_pk_mul_f32 v[0:1], v[0:1], v[64:65] op_sel_hi:[1,0]
	v_sub_f32_e32 v125, v125, v65
	v_sub_f32_e32 v124, v124, v65
	v_sub_f32_e32 v123, v123, v65
	v_sub_f32_e32 v122, v122, v65
	v_sub_f32_e32 v121, v121, v65
	v_sub_f32_e32 v120, v120, v65
	v_sub_f32_e32 v119, v119, v65
	v_sub_f32_e32 v118, v118, v65
	v_sub_f32_e32 v117, v117, v65
	v_sub_f32_e32 v116, v116, v65
	v_sub_f32_e32 v115, v115, v65
	v_sub_f32_e32 v114, v114, v65
	v_sub_f32_e32 v113, v113, v65
	v_sub_f32_e32 v112, v112, v65
	v_sub_f32_e32 v231, v231, v65
	v_sub_f32_e32 v230, v230, v65
	v_sub_f32_e32 v229, v229, v65
	v_sub_f32_e32 v228, v228, v65
	v_sub_f32_e32 v227, v227, v65
	v_sub_f32_e32 v226, v226, v65
	v_sub_f32_e32 v225, v225, v65
	v_sub_f32_e32 v224, v224, v65
	v_sub_f32_e32 v223, v223, v65
	v_sub_f32_e32 v222, v222, v65
	v_sub_f32_e32 v221, v221, v65
	v_sub_f32_e32 v220, v220, v65
	v_sub_f32_e32 v219, v219, v65
	v_sub_f32_e32 v218, v218, v65
	v_sub_f32_e32 v217, v217, v65
	v_sub_f32_e32 v216, v216, v65
	v_add_f32_e32 v81, 0x41000000, v80
	v_mov_b32_e32 v83, v82
	v_mov_b32_e32 v84, v82
	v_mov_b32_e32 v85, v82
	v_mov_b32_e32 v86, v82
	v_mov_b32_e32 v87, v82
	v_mov_b32_e32 v88, v82
	v_mov_b32_e32 v89, v82
	v_mov_b32_e32 v90, v82
	v_mov_b32_e32 v91, v82
	v_mov_b32_e32 v92, v82
	v_mov_b32_e32 v93, v82
	v_mov_b32_e32 v94, v82
	v_mov_b32_e32 v95, v82
	v_mov_b32_e32 v96, v82
	v_mov_b32_e32 v97, v82
	v_mov_b32_e32 v79, v82
	v_mov_b32_e32 v78, v82
	v_mov_b32_e32 v77, v82
	v_mov_b32_e32 v76, v82
	v_mov_b32_e32 v75, v82
	v_mov_b32_e32 v74, v82
	v_mov_b32_e32 v73, v82
	v_mov_b32_e32 v72, v82
	v_mov_b32_e32 v71, v82
	v_mov_b32_e32 v70, v82
	v_mov_b32_e32 v69, v82
	v_mov_b32_e32 v68, v82
	v_mov_b32_e32 v67, v82
	v_mov_b32_e32 v66, v82
	v_mov_b32_e32 v65, v82
	v_mov_b32_e32 v64, v82
	v_mov_b32_e32 v195, v80

.LBB0_429:
	s_add_i32 s8, s76, 0
	v_add_u32_e32 v90, s8, v207
	v_add_u32_e32 v94, s8, v208
	v_add_u32_e32 v194, s8, v209
	s_waitcnt lgkmcnt(1)
	v_mfma_f32_32x32x16_bf16 v[128:143], v[82:85], v[160:163], v[64:79]
	ds_read_b128 v[82:85], v90
	ds_read_b128 v[90:93], v90 offset:4096
	v_exp_f32_e32 v95, v112
	v_exp_f32_e32 v245, v113
	v_exp_f32_e32 v145, v217
	v_exp_f32_e32 v244, v115
	v_exp_f32_e32 v115, v221
	v_cvt_pk_bf16_f32 v112, v95, v245
	s_waitcnt lgkmcnt(2)
	v_mfma_f32_32x32x16_bf16 v[96:111], v[86:89], v[160:163], v[64:79]
	ds_read_b128 v[86:89], v94
	ds_read_b128 v[232:235], v94 offset:4096
	ds_read_b128 v[236:239], v194
	ds_read_b128 v[240:243], v194 offset:4096
	v_exp_f32_e32 v94, v114
	v_exp_f32_e32 v114, v117
	v_exp_f32_e32 v156, v228
	s_add_i32 s8, s77, s76
	v_cvt_pk_bf16_f32 v113, v94, v244
	s_cmpk_eq_i32 s8, 0x2000
	s_waitcnt lgkmcnt(5)
	v_mfma_f32_32x32x16_bf16 v[128:143], v[82:85], v[164:167], v[128:143]
	v_exp_f32_e32 v85, v216
	v_exp_f32_e32 v84, v218
	v_exp_f32_e32 v144, v219
	s_cselect_b32 s9, s71, 0x2000
	v_cvt_pk_bf16_f32 v82, v85, v145
	s_cmpk_lg_i32 s8, 0x6000
	s_cselect_b32 s76, s9, 0
	s_waitcnt lgkmcnt(4)
	v_mfma_f32_32x32x16_bf16 v[96:111], v[90:93], v[164:167], v[96:111]
	v_add_f32_e32 v90, v94, v244
	v_add_f32_e32 v91, v95, v245
	v_add_f32_e32 v92, v84, v144
	v_add_f32_e32 v93, v85, v145
	v_exp_f32_e32 v94, v120
	v_add_f32_e32 v90, v90, v92
	v_add_f32_e32 v91, v91, v93
	v_exp_f32_e32 v92, v116
	v_exp_f32_e32 v93, v220
	s_waitcnt lgkmcnt(3)
	v_mfma_f32_32x32x16_bf16 v[128:143], v[86:89], v[168:171], v[128:143]
	v_add_f32_e32 v87, v90, v91
	v_cvt_pk_bf16_f32 v83, v84, v144
	v_add_f32_e32 v84, v92, v114
	v_add_f32_e32 v85, v93, v115
	v_exp_f32_e32 v86, v119
	v_add_f32_e32 v89, v84, v85
	v_exp_f32_e32 v85, v118
	v_exp_f32_e32 v88, v222
	v_exp_f32_e32 v90, v223
	s_waitcnt lgkmcnt(2)
	v_mfma_f32_32x32x16_bf16 v[96:111], v[232:235], v[168:171], v[96:111]
	v_cvt_pk_bf16_f32 v114, v92, v114
	v_cvt_pk_bf16_f32 v84, v93, v115
	v_add_f32_e32 v95, v85, v86
	v_add_f32_e32 v233, v88, v90
	v_cvt_pk_bf16_f32 v115, v85, v86
	v_cvt_pk_bf16_f32 v85, v88, v90
	ds_read_b64_tr_b16 v[90:91], v213 offset:24576
	ds_read_b64_tr_b16 v[92:93], v213 offset:26624
	v_exp_f32_e32 v232, v121
	v_exp_f32_e32 v88, v224
	v_exp_f32_e32 v86, v225
	ds_read_b64_tr_b16 v[116:117], v214 offset:24576
	ds_read_b64_tr_b16 v[118:119], v214 offset:26624
	ds_read_b64_tr_b16 v[144:145], v213 offset:28672
	ds_read_b64_tr_b16 v[146:147], v213 offset:30720
	v_add_f32_e32 v120, v94, v232
	v_add_f32_e32 v121, v95, v233
	s_waitcnt lgkmcnt(4)
	v_mfma_f32_32x32x16_bf16 v[48:63], v[90:93], v[112:115], v[48:63]
	v_add_f32_e32 v90, v88, v86
	v_add_f32_e32 v91, v89, v87
	v_exp_f32_e32 v234, v122
	v_add_f32_e32 v152, v120, v90
	v_add_f32_e32 v153, v121, v91
	ds_read_b64_tr_b16 v[90:91], v215 offset:24576
	ds_read_b64_tr_b16 v[92:93], v215 offset:26624
	ds_read_b64_tr_b16 v[148:149], v214 offset:28672
	ds_read_b64_tr_b16 v[150:151], v214 offset:30720
	v_exp_f32_e32 v235, v226
	v_exp_f32_e32 v87, v124
	v_exp_f32_e32 v89, v125
	v_mfma_f32_32x32x16_bf16 v[128:143], v[236:239], v[172:175], v[128:143]
	v_exp_f32_e32 v236, v123
	v_exp_f32_e32 v237, v227
	v_add_f32_e32 v239, v152, v153
	v_exp_f32_e32 v238, v231
	s_min_u32 s8, s4, 32
	s_min_u32 s10, s4, 33
	s_lshl_b32 s8, s8, 17
	s_waitcnt lgkmcnt(6)
	v_mfma_f32_32x32x16_bf16 v[32:47], v[116:119], v[112:115], v[32:47]
	ds_read_b64_tr_b16 v[116:117], v248 offset:24576
	ds_read_b64_tr_b16 v[118:119], v248 offset:26624
	ds_read_b64_tr_b16 v[120:121], v215 offset:28672
	ds_read_b64_tr_b16 v[122:123], v215 offset:30720
	ds_read_b64_tr_b16 v[152:153], v248 offset:28672
	ds_read_b64_tr_b16 v[154:155], v248 offset:30720
	s_add_u32 s8, s36, s8
	s_addc_u32 s9, s37, 0
	s_waitcnt lgkmcnt(8)
	v_mfma_f32_32x32x16_bf16 v[16:31], v[90:93], v[112:115], v[16:31]
	v_add_f32_e32 v92, v234, v236
	v_add_f32_e32 v93, v235, v237
	v_cvt_pk_bf16_f32 v90, v94, v232
	v_add_f32_e32 v95, v92, v93
	v_cvt_pk_bf16_f32 v91, v234, v236
	v_cvt_pk_bf16_f32 v92, v87, v89
	v_exp_f32_e32 v94, v230
	s_waitcnt lgkmcnt(4)
	v_mfma_f32_32x32x16_bf16 v[0:15], v[116:119], v[112:115], v[0:15]
	v_exp_f32_e32 v112, v126
	v_exp_f32_e32 v114, v127
	v_add_f32_e32 v113, v87, v89
	v_max_f32_e32 v89, v128, v128
	v_cvt_pk_bf16_f32 v93, v112, v114
	s_nop 1
	v_mfma_f32_32x32x16_bf16 v[48:63], v[144:147], v[90:93], v[48:63]
	v_exp_f32_e32 v144, v229
	v_cvt_pk_bf16_f32 v147, v94, v238
	v_cvt_pk_bf16_f32 v145, v235, v237
	v_add_f32_e32 v115, v156, v144
	v_add_f32_e32 v112, v112, v114
	v_add_f32_e32 v113, v113, v115
	v_add_f32_e32 v114, v94, v238
	v_add_f32_e32 v115, v95, v239
	v_mfma_f32_32x32x16_bf16 v[32:47], v[148:151], v[90:93], v[32:47]
	v_add_f32_e32 v112, v112, v114
	v_add_f32_e32 v113, v113, v115
	v_cvt_pk_bf16_f32 v146, v156, v144
	v_add_f32_e32 v87, v112, v113
	ds_read_b64_tr_b16 v[112:113], v213 offset:32768
	ds_read_b64_tr_b16 v[114:115], v213 offset:34816
	v_add_f32_e32 v194, v196, v87
	v_max_f32_e32 v87, v129, v129
	v_max_f32_e32 v87, v89, v87
	s_waitcnt lgkmcnt(4)
	v_mfma_f32_32x32x16_bf16 v[16:31], v[120:123], v[90:93], v[16:31]
	v_max3_f32 v87, v87, v130, v131
	v_max3_f32 v87, v87, v132, v133
	v_max3_f32 v87, v87, v134, v135
	v_max3_f32 v87, v87, v136, v137
	v_max3_f32 v87, v87, v138, v139
	v_max3_f32 v87, v87, v140, v141
	v_max3_f32 v87, v87, v142, v143
	s_waitcnt lgkmcnt(2)
	v_mfma_f32_32x32x16_bf16 v[0:15], v[152:155], v[90:93], v[0:15]
	ds_read_b64_tr_b16 v[90:91], v214 offset:32768
	ds_read_b64_tr_b16 v[92:93], v214 offset:34816
	ds_read_b64_tr_b16 v[116:117], v213 offset:36864
	ds_read_b64_tr_b16 v[118:119], v213 offset:38912
	v_cvt_pk_bf16_f32 v144, v88, v86
	s_waitcnt lgkmcnt(4)
	v_mfma_f32_32x32x16_bf16 v[48:63], v[112:115], v[82:85], v[48:63]
	ds_read_b64_tr_b16 v[112:113], v215 offset:32768
	ds_read_b64_tr_b16 v[114:115], v215 offset:34816
	ds_read_b64_tr_b16 v[120:121], v214 offset:36864
	ds_read_b64_tr_b16 v[122:123], v214 offset:38912
	s_waitcnt lgkmcnt(6)
	v_mfma_f32_32x32x16_bf16 v[32:47], v[90:93], v[82:85], v[32:47]
	ds_read_b64_tr_b16 v[90:91], v248 offset:32768
	ds_read_b64_tr_b16 v[92:93], v248 offset:34816
	ds_read_b64_tr_b16 v[124:125], v215 offset:36864
	ds_read_b64_tr_b16 v[126:127], v215 offset:38912
	v_mfma_f32_32x32x16_bf16 v[96:111], v[240:243], v[172:175], v[96:111]
	s_waitcnt lgkmcnt(6)
	v_mfma_f32_32x32x16_bf16 v[16:31], v[112:115], v[82:85], v[16:31]
	ds_read_b64_tr_b16 v[112:113], v248 offset:36864
	ds_read_b64_tr_b16 v[114:115], v248 offset:38912
	s_nop 7
	v_max3_f32 v87, v87, v96, v97
	v_max3_f32 v87, v87, v98, v99
	s_waitcnt vmcnt(0)
	s_waitcnt lgkmcnt(0)
	s_barrier
	v_mfma_f32_32x32x16_bf16 v[0:15], v[90:93], v[82:85], v[0:15]
	v_lshl_add_u64 v[82:83], v[180:181], 1, s[8:9]
	s_add_i32 s8, s43, s76
	v_lshl_add_u64 v[82:83], v[82:83], 0, s[24:25]
	s_mov_b32 m0, s8
	s_nop 0
	global_load_lds_dwordx4 v[82:83], off
	s_lshl_b32 s8, s10, 17
	v_max3_f32 v87, v87, v100, v101
	s_add_u32 s8, s26, s8
	v_mfma_f32_32x32x16_bf16 v[48:63], v[116:119], v[144:147], v[48:63]
	v_max3_f32 v87, v87, v102, v103
	s_addc_u32 s9, s27, 0
	v_max3_f32 v87, v87, v104, v105
	s_add_u32 s8, s8, 0x40000
	v_max3_f32 v87, v87, v106, v107
	s_addc_u32 s9, s9, 0
	v_max3_f32 v87, v87, v108, v109
	v_mfma_f32_32x32x16_bf16 v[32:47], v[120:123], v[144:147], v[32:47]
	v_lshl_add_u64 v[82:83], v[176:177], 1, s[8:9]
	s_mov_b32 m0, s65
	s_nop 0
	global_load_lds_dwordx4 v[82:83], off
	v_max3_f32 v87, v87, v110, v111
	v_lshl_add_u64 v[82:83], v[178:179], 1, s[8:9]
	s_mov_b32 m0, s66
	s_nop 0
	global_load_lds_dwordx4 v[82:83], off
	v_add_f32_e32 v87, v195, v87
	v_cmp_gt_f32_e32 vcc, v87, v81
	v_mfma_f32_32x32x16_bf16 v[16:31], v[124:127], v[144:147], v[16:31]
	v_mfma_f32_32x32x16_bf16 v[0:15], v[112:115], v[144:147], v[0:15]
	s_cbranch_vccz .LBB0_423
	ds_bpermute_b32 v82, v204, v87
	v_max_f32_e32 v83, v87, v87
	s_waitcnt lgkmcnt(0)
	v_max_f32_e32 v82, v82, v82
	v_max_f32_e32 v112, v83, v82
	v_cmp_gt_f32_e32 vcc, v112, v81
	s_and_saveexec_b64 s[8:9], vcc
	s_cbranch_execz .LBB0_422
	v_sub_f32_e32 v65, v112, v195
	v_exp_f32_e64 v64, -v65
	v_xor_b32_e32 v80, 0x80000000, v112
	v_mov_b32_e32 v81, v80
	v_sub_f32_e32 v128, v128, v65
	v_mul_f32_e32 v194, v194, v64
	v_pk_mul_f32 v[62:63], v[62:63], v[64:65] op_sel_hi:[1,0]
	v_pk_mul_f32 v[60:61], v[60:61], v[64:65] op_sel_hi:[1,0]
	v_pk_mul_f32 v[58:59], v[58:59], v[64:65] op_sel_hi:[1,0]
	v_pk_mul_f32 v[56:57], v[56:57], v[64:65] op_sel_hi:[1,0]
	v_pk_mul_f32 v[54:55], v[54:55], v[64:65] op_sel_hi:[1,0]
	v_pk_mul_f32 v[52:53], v[52:53], v[64:65] op_sel_hi:[1,0]
	v_pk_mul_f32 v[50:51], v[50:51], v[64:65] op_sel_hi:[1,0]
	v_pk_mul_f32 v[48:49], v[48:49], v[64:65] op_sel_hi:[1,0]
	v_pk_mul_f32 v[46:47], v[46:47], v[64:65] op_sel_hi:[1,0]
	v_pk_mul_f32 v[44:45], v[44:45], v[64:65] op_sel_hi:[1,0]
	v_pk_mul_f32 v[42:43], v[42:43], v[64:65] op_sel_hi:[1,0]
	v_pk_mul_f32 v[40:41], v[40:41], v[64:65] op_sel_hi:[1,0]
	v_pk_mul_f32 v[38:39], v[38:39], v[64:65] op_sel_hi:[1,0]
	v_pk_mul_f32 v[36:37], v[36:37], v[64:65] op_sel_hi:[1,0]
	v_pk_mul_f32 v[34:35], v[34:35], v[64:65] op_sel_hi:[1,0]
	v_pk_mul_f32 v[32:33], v[32:33], v[64:65] op_sel_hi:[1,0]
	v_pk_mul_f32 v[30:31], v[30:31], v[64:65] op_sel_hi:[1,0]
	v_pk_mul_f32 v[28:29], v[28:29], v[64:65] op_sel_hi:[1,0]
	v_pk_mul_f32 v[26:27], v[26:27], v[64:65] op_sel_hi:[1,0]
	v_pk_mul_f32 v[24:25], v[24:25], v[64:65] op_sel_hi:[1,0]
	v_pk_mul_f32 v[22:23], v[22:23], v[64:65] op_sel_hi:[1,0]
	v_pk_mul_f32 v[20:21], v[20:21], v[64:65] op_sel_hi:[1,0]
	v_pk_mul_f32 v[18:19], v[18:19], v[64:65] op_sel_hi:[1,0]
	v_pk_mul_f32 v[16:17], v[16:17], v[64:65] op_sel_hi:[1,0]
	v_pk_mul_f32 v[14:15], v[14:15], v[64:65] op_sel_hi:[1,0]
	v_pk_mul_f32 v[12:13], v[12:13], v[64:65] op_sel_hi:[1,0]
	v_pk_mul_f32 v[10:11], v[10:11], v[64:65] op_sel_hi:[1,0]
	v_pk_mul_f32 v[8:9], v[8:9], v[64:65] op_sel_hi:[1,0]
	v_pk_mul_f32 v[6:7], v[6:7], v[64:65] op_sel_hi:[1,0]
	v_pk_mul_f32 v[4:5], v[4:5], v[64:65] op_sel_hi:[1,0]
	v_pk_mul_f32 v[2:3], v[2:3], v[64:65] op_sel_hi:[1,0]
	v_pk_mul_f32 v[0:1], v[0:1], v[64:65] op_sel_hi:[1,0]
	v_sub_f32_e32 v129, v129, v65
	v_sub_f32_e32 v130, v130, v65
	v_sub_f32_e32 v131, v131, v65
	v_sub_f32_e32 v132, v132, v65
	v_sub_f32_e32 v133, v133, v65
	v_sub_f32_e32 v134, v134, v65
	v_sub_f32_e32 v135, v135, v65
	v_sub_f32_e32 v136, v136, v65
	v_sub_f32_e32 v137, v137, v65
	v_sub_f32_e32 v138, v138, v65
	v_sub_f32_e32 v139, v139, v65
	v_sub_f32_e32 v140, v140, v65
	v_sub_f32_e32 v141, v141, v65
	v_sub_f32_e32 v142, v142, v65
	v_sub_f32_e32 v143, v143, v65
	v_sub_f32_e32 v96, v96, v65
	v_sub_f32_e32 v97, v97, v65
	v_sub_f32_e32 v98, v98, v65
	v_sub_f32_e32 v99, v99, v65
	v_sub_f32_e32 v100, v100, v65
	v_sub_f32_e32 v101, v101, v65
	v_sub_f32_e32 v102, v102, v65
	v_sub_f32_e32 v103, v103, v65
	v_sub_f32_e32 v104, v104, v65
	v_sub_f32_e32 v105, v105, v65
	v_sub_f32_e32 v106, v106, v65
	v_sub_f32_e32 v107, v107, v65
	v_sub_f32_e32 v108, v108, v65
	v_sub_f32_e32 v109, v109, v65
	v_sub_f32_e32 v110, v110, v65
	v_sub_f32_e32 v111, v111, v65
	v_mov_b32_e32 v82, v80
	v_mov_b32_e32 v83, v80
	v_mov_b32_e32 v84, v80
	v_mov_b32_e32 v85, v80
	v_mov_b32_e32 v86, v80
	v_mov_b32_e32 v87, v80
	v_mov_b32_e32 v88, v80
	v_mov_b32_e32 v89, v80
	v_mov_b32_e32 v90, v80
	v_mov_b32_e32 v91, v80
	v_mov_b32_e32 v92, v80
	v_mov_b32_e32 v93, v80
	v_mov_b32_e32 v94, v80
	v_mov_b32_e32 v95, v80
	v_mov_b64_e32 v[64:65], v[80:81]
	v_mov_b32_e32 v195, v112
	v_mov_b64_e32 v[66:67], v[82:83]
	v_mov_b64_e32 v[68:69], v[84:85]
	v_mov_b64_e32 v[70:71], v[86:87]
	v_mov_b64_e32 v[72:73], v[88:89]
	v_mov_b64_e32 v[74:75], v[90:91]
	v_mov_b64_e32 v[76:77], v[92:93]
	v_mov_b64_e32 v[78:79], v[94:95]
	s_branch .LBB0_422
